# attention local row max as two interleaved v_max3 chains (depth 5 instead of 8) on top of v98
# speedup vs baseline: 1.0081x; 1.0075x over previous
.LBB0_323:
	s_nop 10
	v_max3_f32 v0, v80, s18, v81
	v_max3_f32 v255, v88, v89, v90
	v_max3_f32 v0, v0, v82, v83
	v_max3_f32 v255, v255, v91, v92
	v_max3_f32 v0, v0, v84, v85
	v_max3_f32 v255, v255, v93, v94
	v_max3_f32 v0, v0, v86, v87
	v_max3_f32 v2, v0, v255, v95
	v_max3_f32 v255, v0, v255, v95
	s_and_b64 vcc, exec, s[38:39]
	s_waitcnt lgkmcnt(0)
	v_permlane32_swap_b32_e32 v2, v255
	v_max3_f32 v234, v231, v2, v255
	v_sub_f32_e32 v255, v234, v231
	v_cmp_lt_f32_e64 s[98:99], 4.0, v255
	s_nop 1
	v_cndmask_b32_e64 v234, v231, v234, s[98:99]
	v_sub_f32_e32 v2, v81, v234
	v_exp_f32_e32 v14, v2
	v_sub_f32_e32 v2, v82, v234
	v_exp_f32_e32 v232, v2
	v_sub_f32_e32 v2, v83, v234
	v_exp_f32_e32 v236, v2
	v_sub_f32_e32 v2, v84, v234
	v_exp_f32_e32 v237, v2
	v_sub_f32_e32 v2, v85, v234
	v_exp_f32_e32 v238, v2
	v_sub_f32_e32 v2, v86, v234
	v_exp_f32_e32 v239, v2
	v_sub_f32_e32 v2, v87, v234
	v_exp_f32_e32 v240, v2
	v_sub_f32_e32 v2, v88, v234
	v_exp_f32_e32 v241, v2
	v_sub_f32_e32 v2, v89, v234
	v_exp_f32_e32 v242, v2
	v_sub_f32_e32 v2, v90, v234
	v_exp_f32_e32 v243, v2
	v_sub_f32_e32 v2, v91, v234
	v_exp_f32_e32 v244, v2
	v_sub_f32_e32 v2, v92, v234
	v_exp_f32_e32 v245, v2
	v_sub_f32_e32 v2, v93, v234
	v_exp_f32_e32 v246, v2
	v_sub_f32_e32 v2, v94, v234
	v_sub_f32_e32 v0, v80, v234
	v_exp_f32_e32 v247, v2
	v_sub_f32_e32 v2, v95, v234
	v_mfma_f32_32x32x16_bf16 v[80:95], v[168:171], v[112:115], 0
	v_exp_f32_e32 v0, v0
	v_exp_f32_e32 v248, v2
	v_cvt_pk_bf16_f32 v6, v0, v14
	v_cvt_pk_bf16_f32 v7, v232, v236
	v_cvt_pk_bf16_f32 v8, v237, v238
	v_cvt_pk_bf16_f32 v9, v239, v240
	v_cvt_pk_bf16_f32 v2, v241, v242
	v_mfma_f32_32x32x16_bf16 v[80:95], v[164:167], v[116:119], v[80:95]
	v_cvt_pk_bf16_f32 v3, v243, v244
	v_cvt_pk_bf16_f32 v4, v245, v246
	v_cvt_pk_bf16_f32 v5, v247, v248
	v_mfma_f32_32x32x16_bf16 v[80:95], v[10:13], v[120:123], v[80:95]
	v_mfma_f32_32x32x16_bf16 v[80:95], v[160:163], v[124:127], v[80:95]
	s_cbranch_vccnz .LBB0_326
	s_cmp_lt_i32 s3, s62
	s_cselect_b64 s[0:1], -1, 0
	s_cmp_gt_i32 s3, s55
	s_cselect_b64 s[26:27], -1, 0
	s_or_b64 s[0:1], s[0:1], s[26:27]
	s_andn2_b64 vcc, exec, s[0:1]
	s_cbranch_vccnz .LBB0_326
	s_sub_i32 s0, s33, s63
	v_add_u32_e32 v10, s0, v214
	v_cmp_lt_u32_e32 vcc, s66, v10
	v_add_u32_e32 v255, s0, v215
	v_cmp_lt_u32_e64 s[26:27], s66, v255
	v_cndmask_b32_e32 v80, v200, v80, vcc
	v_add_u32_e32 v10, s0, v216
	v_cmp_lt_u32_e32 vcc, s66, v10
	v_cndmask_b32_e64 v81, v200, v81, s[26:27]
	v_add_u32_e32 v255, s0, v217
	v_cmp_lt_u32_e64 s[26:27], s66, v255
	v_cndmask_b32_e32 v82, v200, v82, vcc
	v_add_u32_e32 v10, s0, v218
	v_cmp_lt_u32_e32 vcc, s66, v10
	v_cndmask_b32_e64 v83, v200, v83, s[26:27]
	v_add_u32_e32 v255, s0, v219
	v_cmp_lt_u32_e64 s[26:27], s66, v255
	v_cndmask_b32_e32 v84, v200, v84, vcc
	v_add_u32_e32 v10, s0, v220
	v_cmp_lt_u32_e32 vcc, s66, v10
	v_cndmask_b32_e64 v85, v200, v85, s[26:27]
	v_add_u32_e32 v255, s0, v221
	v_cmp_lt_u32_e64 s[26:27], s66, v255
	v_cndmask_b32_e32 v86, v200, v86, vcc
	v_add_u32_e32 v10, s0, v222
	v_cmp_lt_u32_e32 vcc, s66, v10
	v_cndmask_b32_e64 v87, v200, v87, s[26:27]
	v_add_u32_e32 v255, s0, v223
	v_cmp_lt_u32_e64 s[26:27], s66, v255
	v_cndmask_b32_e32 v88, v200, v88, vcc
	v_add_u32_e32 v10, s0, v224
	v_cmp_lt_u32_e32 vcc, s66, v10
	v_cndmask_b32_e64 v89, v200, v89, s[26:27]
	v_add_u32_e32 v255, s0, v225
	v_cmp_lt_u32_e64 s[26:27], s66, v255
	v_cndmask_b32_e32 v90, v200, v90, vcc
	v_add_u32_e32 v10, s0, v226
	v_cmp_lt_u32_e32 vcc, s66, v10
	v_cndmask_b32_e64 v91, v200, v91, s[26:27]
	v_add_u32_e32 v255, s0, v227
	v_cmp_lt_u32_e64 s[26:27], s66, v255
	v_cndmask_b32_e32 v92, v200, v92, vcc
	v_add_u32_e32 v10, s0, v228
	v_cmp_lt_u32_e32 vcc, s66, v10
	v_cndmask_b32_e64 v93, v200, v93, s[26:27]
	v_add_u32_e32 v255, s0, v229
	v_cmp_lt_u32_e64 s[26:27], s66, v255
	v_cndmask_b32_e32 v94, v200, v94, vcc
	s_nop 0
	v_cndmask_b32_e64 v95, v200, v95, s[26:27]

.Lrs_0:
	v_max3_f32 v0, v80, s18, v81
	v_max3_f32 v255, v88, v89, v90
	v_max3_f32 v0, v0, v82, v83
	v_max3_f32 v255, v255, v91, v92
	v_max3_f32 v0, v0, v84, v85
	v_max3_f32 v255, v255, v93, v94
	v_max3_f32 v0, v0, v86, v87
	v_max3_f32 v10, v0, v255, v95
	v_max3_f32 v255, v0, v255, v95
	s_waitcnt lgkmcnt(0)
	s_nop 0
	v_permlane32_swap_b32_e32 v10, v255
	v_max3_f32 v14, v235, v10, v255
	v_sub_f32_e32 v255, v14, v235
	v_cmp_lt_f32_e64 s[98:99], 4.0, v255
	s_nop 1
	v_cndmask_b32_e64 v14, v235, v14, s[98:99]
	v_sub_f32_e32 v0, v80, v14
	v_exp_f32_e32 v11, v0
	v_sub_f32_e32 v12, v81, v14
	v_exp_f32_e32 v12, v12
	v_sub_f32_e32 v13, v82, v14
	v_exp_f32_e32 v13, v13
	v_sub_f32_e32 v80, v83, v14
	v_exp_f32_e32 v81, v80
	v_sub_f32_e32 v80, v84, v14
	v_add_f32_e32 v0, 0, v11
	v_exp_f32_e32 v82, v80
	v_sub_f32_e32 v80, v85, v14
	v_add_f32_e32 v0, v12, v0
	v_exp_f32_e32 v83, v80
	v_sub_f32_e32 v80, v86, v14
	v_add_f32_e32 v0, v13, v0
	v_exp_f32_e32 v84, v80
	v_sub_f32_e32 v80, v87, v14
	v_add_f32_e32 v0, v81, v0
	v_exp_f32_e32 v85, v80
	v_sub_f32_e32 v80, v88, v14
	v_add_f32_e32 v0, v82, v0
	v_exp_f32_e32 v86, v80
	v_sub_f32_e32 v80, v89, v14
	v_add_f32_e32 v0, v83, v0
	v_exp_f32_e32 v87, v80
	v_sub_f32_e32 v80, v90, v14
	v_add_f32_e32 v0, v84, v0
	v_exp_f32_e32 v88, v80
	v_sub_f32_e32 v80, v91, v14
	v_add_f32_e32 v0, v85, v0
	v_exp_f32_e32 v89, v80
	v_sub_f32_e32 v80, v92, v14
	v_add_f32_e32 v0, v86, v0
	v_exp_f32_e32 v90, v80
	v_sub_f32_e32 v80, v93, v14
	v_add_f32_e32 v0, v87, v0
	v_exp_f32_e32 v91, v80
	v_sub_f32_e32 v80, v94, v14
	v_add_f32_e32 v0, v88, v0
	v_exp_f32_e32 v92, v80
	v_sub_f32_e32 v80, v95, v14
	v_add_f32_e32 v0, v89, v0
	v_exp_f32_e32 v93, v80
	v_add_f32_e32 v0, v90, v0
	v_add_f32_e32 v0, v91, v0
	v_add_f32_e32 v0, v92, v0
	v_add_f32_e32 v0, v93, v0
	s_mov_b64 vcc, s[98:99]
	s_cbranch_vccz .Lrse_1
	v_sub_f32_e32 v10, v235, v14
	v_exp_f32_e32 v10, v10
	s_nop 0
	v_fmac_f32_e32 v0, v15, v10
	v_mul_f32_e32 v46, v10, v46
	v_mul_f32_e32 v47, v10, v47
	v_mul_f32_e32 v44, v10, v44
	v_mul_f32_e32 v45, v10, v45
	v_mul_f32_e32 v42, v10, v42
	v_mul_f32_e32 v43, v10, v43
	v_mul_f32_e32 v40, v10, v40
	v_mul_f32_e32 v41, v10, v41
	v_mul_f32_e32 v38, v10, v38
	v_mul_f32_e32 v39, v10, v39
	v_mul_f32_e32 v36, v10, v36
	v_mul_f32_e32 v37, v10, v37
	v_mul_f32_e32 v34, v10, v34
	v_mul_f32_e32 v35, v10, v35
	v_mul_f32_e32 v32, v10, v32
	v_mul_f32_e32 v33, v10, v33
	v_mul_f32_e32 v30, v10, v30
	v_mul_f32_e32 v31, v10, v31
	v_mul_f32_e32 v28, v10, v28
	v_mul_f32_e32 v29, v10, v29
	v_mul_f32_e32 v26, v10, v26
	v_mul_f32_e32 v27, v10, v27
	v_mul_f32_e32 v24, v10, v24
	v_mul_f32_e32 v25, v10, v25
	v_mul_f32_e32 v22, v10, v22
	v_mul_f32_e32 v23, v10, v23
	v_mul_f32_e32 v20, v10, v20
	v_mul_f32_e32 v21, v10, v21
	v_mul_f32_e32 v18, v10, v18
	v_mul_f32_e32 v19, v10, v19
	v_mul_f32_e32 v16, v10, v16
	v_mul_f32_e32 v17, v10, v17
	s_branch .Lrs_1

.LBB0_344:
	s_nop 10
	v_max3_f32 v2, v80, s18, v81
	v_max3_f32 v255, v88, v89, v90
	v_max3_f32 v2, v2, v82, v83
	v_max3_f32 v255, v255, v91, v92
	v_max3_f32 v2, v2, v84, v85
	v_max3_f32 v255, v255, v93, v94
	v_max3_f32 v2, v2, v86, v87
	v_max3_f32 v3, v2, v255, v95
	v_max3_f32 v255, v2, v255, v95
	s_and_b64 vcc, exec, s[40:41]
	s_waitcnt lgkmcnt(0)
	v_permlane32_swap_b32_e32 v3, v255
	v_max3_f32 v233, v234, v3, v255
	v_sub_f32_e32 v255, v233, v234
	v_cmp_lt_f32_e64 s[98:99], 4.0, v255
	s_nop 1
	v_cndmask_b32_e64 v233, v234, v233, s[98:99]
	v_sub_f32_e32 v2, v80, v233
	v_exp_f32_e32 v235, v2
	v_sub_f32_e32 v2, v81, v233
	v_exp_f32_e32 v236, v2
	v_sub_f32_e32 v2, v82, v233
	v_exp_f32_e32 v237, v2
	v_sub_f32_e32 v2, v83, v233
	v_exp_f32_e32 v238, v2
	v_sub_f32_e32 v2, v84, v233
	v_exp_f32_e32 v239, v2
	v_sub_f32_e32 v2, v85, v233
	v_exp_f32_e32 v240, v2
	v_sub_f32_e32 v2, v86, v233
	v_exp_f32_e32 v241, v2
	v_sub_f32_e32 v2, v87, v233
	v_exp_f32_e32 v242, v2
	v_sub_f32_e32 v2, v88, v233
	v_exp_f32_e32 v243, v2
	v_sub_f32_e32 v2, v89, v233
	v_exp_f32_e32 v244, v2
	v_sub_f32_e32 v2, v90, v233
	v_exp_f32_e32 v245, v2
	v_sub_f32_e32 v2, v91, v233
	v_exp_f32_e32 v246, v2
	v_sub_f32_e32 v2, v92, v233
	v_exp_f32_e32 v247, v2
	v_sub_f32_e32 v2, v93, v233
	v_exp_f32_e32 v248, v2
	v_sub_f32_e32 v2, v94, v233
	v_exp_f32_e32 v249, v2
	v_sub_f32_e32 v2, v95, v233
	v_mfma_f32_32x32x16_bf16 v[80:95], v[168:171], v[112:115], 0
	v_exp_f32_e32 v250, v2
	v_cvt_pk_bf16_f32 v6, v235, v236
	v_cvt_pk_bf16_f32 v7, v237, v238
	v_cvt_pk_bf16_f32 v8, v239, v240
	v_cvt_pk_bf16_f32 v9, v241, v242
	v_cvt_pk_bf16_f32 v2, v243, v244
	v_cvt_pk_bf16_f32 v3, v245, v246
	v_mfma_f32_32x32x16_bf16 v[80:95], v[164:167], v[116:119], v[80:95]
	v_cvt_pk_bf16_f32 v4, v247, v248
	v_cvt_pk_bf16_f32 v5, v249, v250
	v_mfma_f32_32x32x16_bf16 v[80:95], v[10:13], v[120:123], v[80:95]
	v_mfma_f32_32x32x16_bf16 v[80:95], v[160:163], v[124:127], v[80:95]
	s_cbranch_vccnz .LBB0_347
	s_cmp_lt_i32 s3, s62
	s_cselect_b64 s[0:1], -1, 0
	s_cmp_gt_i32 s3, s55
	s_cselect_b64 s[26:27], -1, 0
	s_or_b64 s[0:1], s[0:1], s[26:27]
	s_andn2_b64 vcc, exec, s[0:1]
	s_cbranch_vccnz .LBB0_347
	s_sub_i32 s0, s33, s63
	v_add_u32_e32 v10, s0, v214
	v_cmp_lt_u32_e32 vcc, s66, v10
	v_add_u32_e32 v255, s0, v215
	v_cmp_lt_u32_e64 s[26:27], s66, v255
	v_cndmask_b32_e32 v80, v200, v80, vcc
	v_add_u32_e32 v10, s0, v216
	v_cmp_lt_u32_e32 vcc, s66, v10
	v_cndmask_b32_e64 v81, v200, v81, s[26:27]
	v_add_u32_e32 v255, s0, v217
	v_cmp_lt_u32_e64 s[26:27], s66, v255
	v_cndmask_b32_e32 v82, v200, v82, vcc
	v_add_u32_e32 v10, s0, v218
	v_cmp_lt_u32_e32 vcc, s66, v10
	v_cndmask_b32_e64 v83, v200, v83, s[26:27]
	v_add_u32_e32 v255, s0, v219
	v_cmp_lt_u32_e64 s[26:27], s66, v255
	v_cndmask_b32_e32 v84, v200, v84, vcc
	v_add_u32_e32 v10, s0, v220
	v_cmp_lt_u32_e32 vcc, s66, v10
	v_cndmask_b32_e64 v85, v200, v85, s[26:27]
	v_add_u32_e32 v255, s0, v221
	v_cmp_lt_u32_e64 s[26:27], s66, v255
	v_cndmask_b32_e32 v86, v200, v86, vcc
	v_add_u32_e32 v10, s0, v222
	v_cmp_lt_u32_e32 vcc, s66, v10
	v_cndmask_b32_e64 v87, v200, v87, s[26:27]
	v_add_u32_e32 v255, s0, v223
	v_cmp_lt_u32_e64 s[26:27], s66, v255
	v_cndmask_b32_e32 v88, v200, v88, vcc
	v_add_u32_e32 v10, s0, v224
	v_cmp_lt_u32_e32 vcc, s66, v10
	v_cndmask_b32_e64 v89, v200, v89, s[26:27]
	v_add_u32_e32 v255, s0, v225
	v_cmp_lt_u32_e64 s[26:27], s66, v255
	v_cndmask_b32_e32 v90, v200, v90, vcc
	v_add_u32_e32 v10, s0, v226
	v_cmp_lt_u32_e32 vcc, s66, v10
	v_cndmask_b32_e64 v91, v200, v91, s[26:27]
	v_add_u32_e32 v255, s0, v227
	v_cmp_lt_u32_e64 s[26:27], s66, v255
	v_cndmask_b32_e32 v92, v200, v92, vcc
	v_add_u32_e32 v10, s0, v228
	v_cmp_lt_u32_e32 vcc, s66, v10
	v_cndmask_b32_e64 v93, v200, v93, s[26:27]
	v_add_u32_e32 v255, s0, v229
	v_cmp_lt_u32_e64 s[26:27], s66, v255
	v_cndmask_b32_e32 v94, v200, v94, vcc
	s_nop 0
	v_cndmask_b32_e64 v95, v200, v95, s[26:27]

.Lrs_2:
	v_max3_f32 v10, v80, s18, v81
	v_max3_f32 v255, v88, v89, v90
	v_max3_f32 v10, v10, v82, v83
	v_max3_f32 v255, v255, v91, v92
	v_max3_f32 v10, v10, v84, v85
	v_max3_f32 v255, v255, v93, v94
	v_max3_f32 v10, v10, v86, v87
	v_max3_f32 v11, v10, v255, v95
	v_max3_f32 v255, v10, v255, v95
	v_mov_b32_e32 v232, v160
	s_waitcnt lgkmcnt(0)
	v_permlane32_swap_b32_e32 v11, v255
	v_max3_f32 v161, v14, v11, v255
	v_sub_f32_e32 v255, v161, v14
	v_cmp_lt_f32_e64 s[98:99], 4.0, v255
	s_nop 1
	v_cndmask_b32_e64 v161, v14, v161, s[98:99]
	v_sub_f32_e32 v11, v80, v161
	v_exp_f32_e32 v11, v11
	v_sub_f32_e32 v13, v81, v161
	v_sub_f32_e32 v10, v14, v161
	v_exp_f32_e32 v13, v13
	v_sub_f32_e32 v14, v82, v161
	v_exp_f32_e32 v14, v14
	v_sub_f32_e32 v80, v83, v161
	v_exp_f32_e32 v81, v80
	v_sub_f32_e32 v80, v84, v161
	v_add_f32_e32 v12, 0, v11
	v_exp_f32_e32 v82, v80
	v_sub_f32_e32 v80, v85, v161
	v_add_f32_e32 v12, v13, v12
	v_exp_f32_e32 v83, v80
	v_sub_f32_e32 v80, v86, v161
	v_add_f32_e32 v12, v14, v12
	v_exp_f32_e32 v85, v80
	v_sub_f32_e32 v80, v87, v161
	v_add_f32_e32 v12, v81, v12
	v_exp_f32_e32 v86, v80
	v_sub_f32_e32 v80, v88, v161
	v_add_f32_e32 v12, v82, v12
	v_exp_f32_e32 v87, v80
	v_sub_f32_e32 v80, v89, v161
	v_add_f32_e32 v12, v83, v12
	v_exp_f32_e32 v88, v80
	v_sub_f32_e32 v80, v90, v161
	v_add_f32_e32 v12, v85, v12
	v_exp_f32_e32 v89, v80
	v_sub_f32_e32 v80, v91, v161
	v_add_f32_e32 v12, v86, v12
	v_exp_f32_e32 v90, v80
	v_sub_f32_e32 v80, v92, v161
	v_add_f32_e32 v12, v87, v12
	v_exp_f32_e32 v91, v80
	v_sub_f32_e32 v80, v93, v161
	v_add_f32_e32 v12, v88, v12
	v_exp_f32_e32 v92, v80
	v_sub_f32_e32 v80, v94, v161
	v_add_f32_e32 v12, v89, v12
	v_exp_f32_e32 v93, v80
	v_sub_f32_e32 v80, v95, v161
	v_add_f32_e32 v12, v90, v12
	v_exp_f32_e32 v94, v80
	v_add_f32_e32 v12, v91, v12
	v_add_f32_e32 v12, v92, v12
	v_add_f32_e32 v12, v93, v12
	v_add_f32_e32 v84, v94, v12
	s_mov_b64 vcc, s[98:99]
	s_cbranch_vccz .Lrse_3
	v_exp_f32_e32 v10, v10
	s_nop 0
	v_fmac_f32_e32 v84, v0, v10
	v_mul_f32_e32 v46, v10, v46
	v_mul_f32_e32 v47, v10, v47
	v_mul_f32_e32 v44, v10, v44
	v_mul_f32_e32 v45, v10, v45
	v_mul_f32_e32 v42, v10, v42
	v_mul_f32_e32 v43, v10, v43
	v_mul_f32_e32 v40, v10, v40
	v_mul_f32_e32 v41, v10, v41
	v_mul_f32_e32 v38, v10, v38
	v_mul_f32_e32 v39, v10, v39
	v_mul_f32_e32 v36, v10, v36
	v_mul_f32_e32 v37, v10, v37
	v_mul_f32_e32 v34, v10, v34
	v_mul_f32_e32 v35, v10, v35
	v_mul_f32_e32 v32, v10, v32
	v_mul_f32_e32 v33, v10, v33
	v_mul_f32_e32 v30, v10, v30
	v_mul_f32_e32 v31, v10, v31
	v_mul_f32_e32 v28, v10, v28
	v_mul_f32_e32 v29, v10, v29
	v_mul_f32_e32 v26, v10, v26
	v_mul_f32_e32 v27, v10, v27
	v_mul_f32_e32 v24, v10, v24
	v_mul_f32_e32 v25, v10, v25
	v_mul_f32_e32 v22, v10, v22
	v_mul_f32_e32 v23, v10, v23
	v_mul_f32_e32 v20, v10, v20
	v_mul_f32_e32 v21, v10, v21
	v_mul_f32_e32 v18, v10, v18
	v_mul_f32_e32 v19, v10, v19
	v_mul_f32_e32 v16, v10, v16
	v_mul_f32_e32 v17, v10, v17
	s_branch .Lrs_3

.LBB0_362:
	s_nop 10
	v_max3_f32 v2, v80, s18, v81
	v_max3_f32 v255, v88, v89, v90
	v_max3_f32 v2, v2, v82, v83
	v_max3_f32 v255, v255, v91, v92
	v_max3_f32 v2, v2, v84, v85
	v_max3_f32 v255, v255, v93, v94
	v_max3_f32 v2, v2, v86, v87
	v_max3_f32 v3, v2, v255, v95
	v_max3_f32 v255, v2, v255, v95
	s_and_b64 vcc, exec, s[40:41]
	s_waitcnt lgkmcnt(0)
	v_permlane32_swap_b32_e32 v3, v255
	v_max3_f32 v234, v233, v3, v255
	v_sub_f32_e32 v255, v234, v233
	v_cmp_lt_f32_e64 s[98:99], 4.0, v255
	s_nop 1
	v_cndmask_b32_e64 v234, v233, v234, s[98:99]
	v_sub_f32_e32 v2, v80, v234
	v_exp_f32_e32 v235, v2
	v_sub_f32_e32 v2, v81, v234
	v_exp_f32_e32 v236, v2
	v_sub_f32_e32 v2, v82, v234
	v_exp_f32_e32 v237, v2
	v_sub_f32_e32 v2, v83, v234
	v_exp_f32_e32 v238, v2
	v_sub_f32_e32 v2, v84, v234
	v_exp_f32_e32 v239, v2
	v_sub_f32_e32 v2, v85, v234
	v_exp_f32_e32 v240, v2
	v_sub_f32_e32 v2, v86, v234
	v_exp_f32_e32 v241, v2
	v_sub_f32_e32 v2, v87, v234
	v_exp_f32_e32 v242, v2
	v_sub_f32_e32 v2, v88, v234
	v_exp_f32_e32 v243, v2
	v_sub_f32_e32 v2, v89, v234
	v_exp_f32_e32 v244, v2
	v_sub_f32_e32 v2, v90, v234
	v_exp_f32_e32 v245, v2
	v_sub_f32_e32 v2, v91, v234
	v_exp_f32_e32 v246, v2
	v_sub_f32_e32 v2, v92, v234
	v_exp_f32_e32 v247, v2
	v_sub_f32_e32 v2, v93, v234
	v_exp_f32_e32 v248, v2
	v_sub_f32_e32 v2, v94, v234
	v_exp_f32_e32 v249, v2
	v_sub_f32_e32 v2, v95, v234
	v_mfma_f32_32x32x16_bf16 v[80:95], v[168:171], v[112:115], 0
	v_exp_f32_e32 v250, v2
	v_cvt_pk_bf16_f32 v6, v235, v236
	v_cvt_pk_bf16_f32 v7, v237, v238
	v_cvt_pk_bf16_f32 v8, v239, v240
	v_cvt_pk_bf16_f32 v9, v241, v242
	v_cvt_pk_bf16_f32 v2, v243, v244
	v_cvt_pk_bf16_f32 v3, v245, v246
	v_mfma_f32_32x32x16_bf16 v[80:95], v[164:167], v[116:119], v[80:95]
	v_cvt_pk_bf16_f32 v4, v247, v248
	v_cvt_pk_bf16_f32 v5, v249, v250
	v_mfma_f32_32x32x16_bf16 v[80:95], v[10:13], v[120:123], v[80:95]
	v_mfma_f32_32x32x16_bf16 v[80:95], v[160:163], v[124:127], v[80:95]
	s_cbranch_vccnz .LBB0_365
	s_cmp_lt_i32 s3, s62
	s_cselect_b64 s[0:1], -1, 0
	s_cmp_gt_i32 s3, s55
	s_cselect_b64 s[26:27], -1, 0
	s_or_b64 s[0:1], s[0:1], s[26:27]
	s_andn2_b64 vcc, exec, s[0:1]
	s_cbranch_vccnz .LBB0_365
	s_sub_i32 s0, s33, s63
	v_add_u32_e32 v10, s0, v214
	v_cmp_lt_u32_e32 vcc, s66, v10
	v_add_u32_e32 v255, s0, v215
	v_cmp_lt_u32_e64 s[26:27], s66, v255
	v_cndmask_b32_e32 v80, v200, v80, vcc
	v_add_u32_e32 v10, s0, v216
	v_cmp_lt_u32_e32 vcc, s66, v10
	v_cndmask_b32_e64 v81, v200, v81, s[26:27]
	v_add_u32_e32 v255, s0, v217
	v_cmp_lt_u32_e64 s[26:27], s66, v255
	v_cndmask_b32_e32 v82, v200, v82, vcc
	v_add_u32_e32 v10, s0, v218
	v_cmp_lt_u32_e32 vcc, s66, v10
	v_cndmask_b32_e64 v83, v200, v83, s[26:27]
	v_add_u32_e32 v255, s0, v219
	v_cmp_lt_u32_e64 s[26:27], s66, v255
	v_cndmask_b32_e32 v84, v200, v84, vcc
	v_add_u32_e32 v10, s0, v220
	v_cmp_lt_u32_e32 vcc, s66, v10
	v_cndmask_b32_e64 v85, v200, v85, s[26:27]
	v_add_u32_e32 v255, s0, v221
	v_cmp_lt_u32_e64 s[26:27], s66, v255
	v_cndmask_b32_e32 v86, v200, v86, vcc
	v_add_u32_e32 v10, s0, v222
	v_cmp_lt_u32_e32 vcc, s66, v10
	v_cndmask_b32_e64 v87, v200, v87, s[26:27]
	v_add_u32_e32 v255, s0, v223
	v_cmp_lt_u32_e64 s[26:27], s66, v255
	v_cndmask_b32_e32 v88, v200, v88, vcc
	v_add_u32_e32 v10, s0, v224
	v_cmp_lt_u32_e32 vcc, s66, v10
	v_cndmask_b32_e64 v89, v200, v89, s[26:27]
	v_add_u32_e32 v255, s0, v225
	v_cmp_lt_u32_e64 s[26:27], s66, v255
	v_cndmask_b32_e32 v90, v200, v90, vcc
	v_add_u32_e32 v10, s0, v226
	v_cmp_lt_u32_e32 vcc, s66, v10
	v_cndmask_b32_e64 v91, v200, v91, s[26:27]
	v_add_u32_e32 v255, s0, v227
	v_cmp_lt_u32_e64 s[26:27], s66, v255
	v_cndmask_b32_e32 v92, v200, v92, vcc
	v_add_u32_e32 v10, s0, v228
	v_cmp_lt_u32_e32 vcc, s66, v10
	v_cndmask_b32_e64 v93, v200, v93, s[26:27]
	v_add_u32_e32 v255, s0, v229
	v_cmp_lt_u32_e64 s[26:27], s66, v255
	v_cndmask_b32_e32 v94, v200, v94, vcc
	s_nop 0
	v_cndmask_b32_e64 v95, v200, v95, s[26:27]

.LBB0_378:
	s_nop 10
	v_max3_f32 v2, v80, s18, v81
	v_max3_f32 v255, v88, v89, v90
	v_max3_f32 v2, v2, v82, v83
	v_max3_f32 v255, v255, v91, v92
	v_max3_f32 v2, v2, v84, v85
	v_max3_f32 v255, v255, v93, v94
	v_max3_f32 v2, v2, v86, v87
	v_max3_f32 v3, v2, v255, v95
	v_max3_f32 v255, v2, v255, v95
	s_and_b64 vcc, exec, s[38:39]
	s_waitcnt lgkmcnt(0)
	v_permlane32_swap_b32_e32 v3, v255
	v_max3_f32 v231, v234, v3, v255
	v_sub_f32_e32 v255, v231, v234
	v_cmp_lt_f32_e64 s[98:99], 4.0, v255
	s_nop 1
	v_cndmask_b32_e64 v231, v234, v231, s[98:99]
	v_sub_f32_e32 v2, v80, v231
	v_exp_f32_e32 v15, v2
	v_sub_f32_e32 v2, v81, v231
	v_exp_f32_e32 v233, v2
	v_sub_f32_e32 v2, v82, v231
	v_exp_f32_e32 v235, v2
	v_sub_f32_e32 v2, v83, v231
	v_exp_f32_e32 v236, v2
	v_sub_f32_e32 v2, v84, v231
	v_exp_f32_e32 v237, v2
	v_sub_f32_e32 v2, v85, v231
	v_exp_f32_e32 v238, v2
	v_sub_f32_e32 v2, v86, v231
	v_exp_f32_e32 v239, v2
	v_sub_f32_e32 v2, v87, v231
	v_exp_f32_e32 v240, v2
	v_sub_f32_e32 v2, v88, v231
	v_exp_f32_e32 v241, v2
	v_sub_f32_e32 v2, v89, v231
	v_exp_f32_e32 v242, v2
	v_sub_f32_e32 v2, v90, v231
	v_exp_f32_e32 v243, v2
	v_sub_f32_e32 v2, v91, v231
	v_exp_f32_e32 v244, v2
	v_sub_f32_e32 v2, v92, v231
	v_exp_f32_e32 v245, v2
	v_sub_f32_e32 v2, v93, v231
	v_exp_f32_e32 v246, v2
	v_sub_f32_e32 v2, v94, v231
	v_exp_f32_e32 v247, v2
	v_sub_f32_e32 v2, v95, v231
	v_mfma_f32_32x32x16_bf16 v[80:95], v[168:171], v[112:115], 0
	v_exp_f32_e32 v248, v2
	v_cvt_pk_bf16_f32 v6, v15, v233
	v_cvt_pk_bf16_f32 v7, v235, v236
	v_cvt_pk_bf16_f32 v8, v237, v238
	v_cvt_pk_bf16_f32 v9, v239, v240
	v_cvt_pk_bf16_f32 v2, v241, v242
	v_cvt_pk_bf16_f32 v3, v243, v244
	v_mfma_f32_32x32x16_bf16 v[80:95], v[164:167], v[116:119], v[80:95]
	v_cvt_pk_bf16_f32 v4, v245, v246
	v_cvt_pk_bf16_f32 v5, v247, v248
	v_mfma_f32_32x32x16_bf16 v[80:95], v[10:13], v[120:123], v[80:95]
	v_mfma_f32_32x32x16_bf16 v[80:95], v[160:163], v[124:127], v[80:95]
	s_cbranch_vccnz .LBB0_381
	s_cmp_lt_i32 s3, s62
	s_cselect_b64 s[0:1], -1, 0
	s_cmp_gt_i32 s3, s55
	s_cselect_b64 s[26:27], -1, 0
	s_or_b64 s[0:1], s[0:1], s[26:27]
	s_andn2_b64 vcc, exec, s[0:1]
	s_cbranch_vccnz .LBB0_381
	s_sub_i32 s0, s2, s63
	v_add_u32_e32 v10, s0, v214
	v_cmp_lt_u32_e32 vcc, s66, v10
	v_add_u32_e32 v255, s0, v215
	v_cmp_lt_u32_e64 s[26:27], s66, v255
	v_cndmask_b32_e32 v80, v200, v80, vcc
	v_add_u32_e32 v10, s0, v216
	v_cmp_lt_u32_e32 vcc, s66, v10
	v_cndmask_b32_e64 v81, v200, v81, s[26:27]
	v_add_u32_e32 v255, s0, v217
	v_cmp_lt_u32_e64 s[26:27], s66, v255
	v_cndmask_b32_e32 v82, v200, v82, vcc
	v_add_u32_e32 v10, s0, v218
	v_cmp_lt_u32_e32 vcc, s66, v10
	v_cndmask_b32_e64 v83, v200, v83, s[26:27]
	v_add_u32_e32 v255, s0, v219
	v_cmp_lt_u32_e64 s[26:27], s66, v255
	v_cndmask_b32_e32 v84, v200, v84, vcc
	v_add_u32_e32 v10, s0, v220
	v_cmp_lt_u32_e32 vcc, s66, v10
	v_cndmask_b32_e64 v85, v200, v85, s[26:27]
	v_add_u32_e32 v255, s0, v221
	v_cmp_lt_u32_e64 s[26:27], s66, v255
	v_cndmask_b32_e32 v86, v200, v86, vcc
	v_add_u32_e32 v10, s0, v222
	v_cmp_lt_u32_e32 vcc, s66, v10
	v_cndmask_b32_e64 v87, v200, v87, s[26:27]
	v_add_u32_e32 v255, s0, v223
	v_cmp_lt_u32_e64 s[26:27], s66, v255
	v_cndmask_b32_e32 v88, v200, v88, vcc
	v_add_u32_e32 v10, s0, v224
	v_cmp_lt_u32_e32 vcc, s66, v10
	v_cndmask_b32_e64 v89, v200, v89, s[26:27]
	v_add_u32_e32 v255, s0, v225
	v_cmp_lt_u32_e64 s[26:27], s66, v255
	v_cndmask_b32_e32 v90, v200, v90, vcc
	v_add_u32_e32 v10, s0, v226
	v_cmp_lt_u32_e32 vcc, s66, v10
	v_cndmask_b32_e64 v91, v200, v91, s[26:27]
	v_add_u32_e32 v255, s0, v227
	v_cmp_lt_u32_e64 s[26:27], s66, v255
	v_cndmask_b32_e32 v92, v200, v92, vcc
	v_add_u32_e32 v10, s0, v228
	v_cmp_lt_u32_e32 vcc, s66, v10
	v_cndmask_b32_e64 v93, v200, v93, s[26:27]
	v_add_u32_e32 v255, s0, v229
	v_cmp_lt_u32_e64 s[26:27], s66, v255
	v_cndmask_b32_e32 v94, v200, v94, vcc
	s_nop 0
	v_cndmask_b32_e64 v95, v200, v95, s[26:27]

.Lrs_6:
	v_max3_f32 v10, v80, s18, v81
	v_max3_f32 v255, v88, v89, v90
	v_max3_f32 v10, v10, v82, v83
	v_max3_f32 v255, v255, v91, v92
	v_max3_f32 v10, v10, v84, v85
	v_max3_f32 v255, v255, v93, v94
	v_max3_f32 v10, v10, v86, v87
	v_max3_f32 v11, v10, v255, v95
	v_max3_f32 v255, v10, v255, v95
	s_waitcnt lgkmcnt(0)
	s_nop 0
	v_permlane32_swap_b32_e32 v11, v255
	v_max3_f32 v235, v14, v11, v255
	v_sub_f32_e32 v255, v235, v14
	v_cmp_lt_f32_e64 s[98:99], 4.0, v255
	s_nop 1
	v_cndmask_b32_e64 v235, v14, v235, s[98:99]
	v_sub_f32_e32 v11, v80, v235
	v_exp_f32_e32 v11, v11
	v_sub_f32_e32 v13, v81, v235
	v_sub_f32_e32 v10, v14, v235
	v_exp_f32_e32 v13, v13
	v_sub_f32_e32 v14, v82, v235
	v_exp_f32_e32 v14, v14
	v_sub_f32_e32 v15, v83, v235
	v_exp_f32_e32 v81, v15
	v_sub_f32_e32 v15, v84, v235
	v_add_f32_e32 v12, 0, v11
	v_exp_f32_e32 v82, v15
	v_sub_f32_e32 v15, v85, v235
	v_add_f32_e32 v12, v13, v12
	v_exp_f32_e32 v83, v15
	v_sub_f32_e32 v15, v86, v235
	v_add_f32_e32 v12, v14, v12
	v_exp_f32_e32 v84, v15
	v_sub_f32_e32 v15, v87, v235
	v_add_f32_e32 v12, v81, v12
	v_exp_f32_e32 v85, v15
	v_sub_f32_e32 v15, v88, v235
	v_add_f32_e32 v12, v82, v12
	v_exp_f32_e32 v86, v15
	v_sub_f32_e32 v15, v89, v235
	v_add_f32_e32 v12, v83, v12
	v_exp_f32_e32 v87, v15
	v_sub_f32_e32 v15, v90, v235
	v_add_f32_e32 v12, v84, v12
	v_exp_f32_e32 v88, v15
	v_sub_f32_e32 v15, v91, v235
	v_add_f32_e32 v12, v85, v12
	v_exp_f32_e32 v89, v15
	v_sub_f32_e32 v15, v92, v235
	v_add_f32_e32 v12, v86, v12
	v_exp_f32_e32 v90, v15
	v_sub_f32_e32 v15, v93, v235
	v_add_f32_e32 v12, v87, v12
	v_exp_f32_e32 v91, v15
	v_sub_f32_e32 v15, v94, v235
	v_add_f32_e32 v12, v88, v12
	v_exp_f32_e32 v92, v15
	v_sub_f32_e32 v15, v95, v235
	v_add_f32_e32 v12, v89, v12
	v_exp_f32_e32 v93, v15
	v_add_f32_e32 v12, v90, v12
	v_add_f32_e32 v12, v91, v12
	v_add_f32_e32 v12, v92, v12
	v_add_f32_e32 v15, v93, v12
	s_mov_b64 vcc, s[98:99]
	s_cbranch_vccz .Lrse_7
	v_exp_f32_e32 v10, v10
	s_nop 0
	v_fmac_f32_e32 v15, v0, v10
	v_mul_f32_e32 v46, v10, v46
	v_mul_f32_e32 v47, v10, v47
	v_mul_f32_e32 v44, v10, v44
	v_mul_f32_e32 v45, v10, v45
	v_mul_f32_e32 v42, v10, v42
	v_mul_f32_e32 v43, v10, v43
	v_mul_f32_e32 v40, v10, v40
	v_mul_f32_e32 v41, v10, v41
	v_mul_f32_e32 v38, v10, v38
	v_mul_f32_e32 v39, v10, v39
	v_mul_f32_e32 v36, v10, v36
	v_mul_f32_e32 v37, v10, v37
	v_mul_f32_e32 v34, v10, v34
	v_mul_f32_e32 v35, v10, v35
	v_mul_f32_e32 v32, v10, v32
	v_mul_f32_e32 v33, v10, v33
	v_mul_f32_e32 v30, v10, v30
	v_mul_f32_e32 v31, v10, v31
	v_mul_f32_e32 v28, v10, v28
	v_mul_f32_e32 v29, v10, v29
	v_mul_f32_e32 v26, v10, v26
	v_mul_f32_e32 v27, v10, v27
	v_mul_f32_e32 v24, v10, v24
	v_mul_f32_e32 v25, v10, v25
	v_mul_f32_e32 v22, v10, v22
	v_mul_f32_e32 v23, v10, v23
	v_mul_f32_e32 v20, v10, v20
	v_mul_f32_e32 v21, v10, v21
	v_mul_f32_e32 v18, v10, v18
	v_mul_f32_e32 v19, v10, v19
	v_mul_f32_e32 v16, v10, v16
	v_mul_f32_e32 v17, v10, v17
	s_branch .Lrs_7
